# one static s_setprio 1 for waves 4-7 during the attention phase (reset after), to de-phase the two waves of each SIMD
# speedup vs baseline: 1.0003x; 1.0003x over previous
; #define LAS __attribute__((address_space(3)))
; #define LS(x) asm volatile("" : "+s"(x))
; #define PH_ENTER() int tid = tid0, blk = blk0, G = G0; unsigned long long zoff_ = 0ull; LV(tid); LS(blk); LS(G); LS(zoff_); unsigned char* ws = ws0 + zoff_; \
;         const int lane = tid & 63, wave = __builtin_amdgcn_readfirstlane(tid >> 6), gw = blk * NWAVES + wave, ngw = G * NWAVES; (void)lane; (void)gw; (void)ngw
; __device__ __forceinline__ void attn_phase(const bf16_t* FQ, const bf16_t* FK, const bf16_t* FV, const float* cum, const float* norms, bf16_t* Y, unsigned* qctr, unsigned* flags, float* parts, lptr lds, int tid_) {
;     LAS int* sh = (LAS int*)(lds + OFF_SH);
;     for (;;) {
;         int tid = tid_; asm volatile("" : "+v"(tid));
;         const int wid = __builtin_amdgcn_readfirstlane(tid >> 6), lane = tid & 63;
;         __syncthreads();
;         if (tid == 0) sh[0] = (int)__hip_atomic_fetch_add(qctr, 1u, __ATOMIC_RELAXED, __HIP_MEMORY_SCOPE_AGENT);
; template <unsigned PHMASK> __global__ void __launch_bounds__(NTHREADS, 2) fwd(Args a) {
;     ...
;             { PH_ENTER(); int l = l0; LS(l);
;               fa::attn_phase((const bf16_t*)(ws + WS_FQ), (const bf16_t*)(ws + WS_FK), (const bf16_t*)(ws + WS_FV), (const float*)(ws + WS_CUM), (const float*)(ws + WS_NORM), (bf16_t*)(ws + WS_Y),
;                              (unsigned*)(ws + WS_CTL) + CW_QUEUE + 64 * (2 * l + (rep_ & 1)), (unsigned*)(ws + WS_CTL) + CW_FLAGS + (size_t)l * 1024, (float*)(ws + WS_PART), (fa::lptr)lds, tid); }
.LBB0_820:
	v_readfirstlane_b32 s0, v0
	s_nop 1
	s_cmp_lt_u32 s0, 0x100
	s_cbranch_scc1 .Lattn_prio_done
	s_setprio 1

; __device__ __forceinline__ unsigned xb_add(unsigned* p, unsigned v) { return __hip_atomic_fetch_add(p, v, __ATOMIC_RELAXED, __HIP_MEMORY_SCOPE_AGENT); }
; __device__ __forceinline__ void xcd_barrier(const XcdBarrier& b) {
;     asm volatile("s_waitcnt vmcnt(0)" ::: "memory");
;     __syncthreads();
;     if (threadIdx.x == 0) {
;         unsigned long long zb_ = 0ull; asm volatile("" : "+s"(zb_));
;         unsigned* bar = b.bar + zb_; unsigned bx = b.x; asm volatile("" : "+s"(bx));
;         __builtin_amdgcn_s_waitcnt(0);
;         unsigned nloc = b.st[0], nx = b.st[1];
;         if (nloc == 0u) { xcd_barrier_complete(bar, bx, nloc, nx); b.st[0] = nloc; b.st[1] = nx; }
;         const unsigned old = xb_add(&bar[XB_XSUB(bx)], 1u);
.LBB0_950:
	s_setprio 0
	v_readlane_b32 s0, v254, 18
	v_readlane_b32 s1, v254, 19
	s_andn2_b64 vcc, exec, s[0:1]
	s_cbranch_vccnz .LBB0_1004
	s_waitcnt vmcnt(0)
	s_waitcnt vmcnt(63) expcnt(7) lgkmcnt(15)
	s_barrier
	s_mov_b64 s[0:1], exec
	v_readlane_b32 s4, v254, 20
	v_readlane_b32 s5, v254, 21
	s_and_b64 s[4:5], s[0:1], s[4:5]
	s_mov_b64 exec, s[4:5]
	s_cbranch_execz .LBB0_1003
	v_readlane_b32 s6, v254, 15
	s_mov_b64 s[4:5], 0
	v_readlane_b32 s20, v254, 8
	v_mov_b32_e32 v1, s6
	s_waitcnt vmcnt(0) expcnt(0) lgkmcnt(0)
	ds_read_b32 v3, v1
	ds_read_b32 v2, v1 offset:4
	s_lshl_b64 s[4:5], s[4:5], 2
	v_readlane_b32 s6, v254, 6
	v_readlane_b32 s7, v254, 7
	s_add_u32 s4, s6, s4
	s_waitcnt lgkmcnt(1)
	v_cmp_ne_u32_e32 vcc, 0, v3
	s_addc_u32 s5, s7, s5
	s_cbranch_vccnz .LBB0_967
	v_readlane_b32 s6, v254, 1
	v_readlane_b32 s7, v254, 2
	s_load_dwordx2 s[10:11], s[6:7], 0x4
	s_add_u32 s6, s4, 0x1000
	s_addc_u32 s7, s5, 0
	s_add_u32 s8, s4, 0x1100
	s_addc_u32 s9, s5, 0
	v_readlane_b32 s12, v254, 3
	s_waitcnt lgkmcnt(0)
	s_mul_i32 s21, s10, s12
	s_add_u32 s10, s4, 0x1200
	s_mul_i32 s21, s21, s11
	s_addc_u32 s11, s5, 0
	s_add_u32 s12, s4, 0x1300
	s_addc_u32 s13, s5, 0
	s_mov_b32 s22, 1
	s_branch .LBB0_955
